# v9: v7 + first QK MFMAs of the odd tile read the running reference from v[66:81] directly (no per-tile copy) + diff-attention tiles whose scores are all below -192 (exp2 weights exactly 0) skip their
# speedup vs baseline: 1.0153x; 1.0026x over previous
; template <int DQK, int DV, bool BIAS> ...
;     ...
;     for (int g = 0; g < NG; ++g) {
;         const int pair = g & 1;
;         __syncthreads();
;         if (g + 1 < NG) {
;     ...
;             l += ls;
.Lend2_p4a1:
	s_add_u32 s6, s6, 0xca000
	s_addc_u32 s7, s7, 0
	s_add_i32 s51, s51, 2
	v_add_f32_e32 v151, v158, v82
	s_cmp_lg_u32 s6, 0x1940000
	v_add_u32_e32 v173, 0x80, v173
	s_cbranch_scc0 .LBB0_586

; #define LAS __attribute__((address_space(3)))
; __device__ __forceinline__ float max3f(float a, float b, float c) { float r; asm("v_max3_f32 %0, %1, %2, %3" : "=v"(r) : "v"(a), "v"(b), "v"(c)); return r; }
; template <int DQK, int DV, bool BIAS> ...
;     ...
;         const LAS unsigned char* kb = lds + buf * KBUF + r32 * KP + hi * 16;
; #pragma unroll
;         for (int ks = 0; ks < NKS; ++ks) {
;             const bf16x8 k0 = *(const LAS bf16x8*)(kb + ks * 32), k1 = *(const LAS bf16x8*)(kb + 32 * KP + ks * 32);
;             if (ks == 0) { p0 = __builtin_amdgcn_mfma_f32_32x32x16_bf16(k0, qf[0], negm, 0, 0, 0); p1 = __builtin_amdgcn_mfma_f32_32x32x16_bf16(k1, qf[0], negm, 0, 0, 0); }
;             else { p0 = __builtin_amdgcn_mfma_f32_32x32x16_bf16(k0, qf[ks], p0, 0, 0, 0); p1 = __builtin_amdgcn_mfma_f32_32x32x16_bf16(k1, qf[ks], p1, 0, 0, 0); }
;         }
;         if (BIAS) {
;             asm volatile("s_nop 15\n\ts_nop 7" : "+v"(p0), "+v"(p1));
;             const float d0 = qp - (float)(t * 64 + 4 * hi);
; #pragma unroll
;             for (int r = 0; r < 16; ++r) { const float dk = d0 - (float)((r & 3) + 8 * (r >> 2)); p0[r] = p0[r] - sl2 * fabsf(dk); p1[r] = p1[r] - sl2 * fabsf(dk - 32.f); }
;         } else {
;             asm volatile("s_nop 15\n\ts_nop 7" : "+v"(p0), "+v"(p1));
;         }
;         float mxa = max3f(p0[0], p0[1], p1[0]), mxb = max3f(p0[2], p0[3], p1[1]); mxa = max3f(mxa, p1[2], p1[3]);
; #pragma unroll
;         for (int r = 4; r < 16; r += 4) { mxa = max3f(mxa, p0[r], p0[r + 1]); mxb = max3f(mxb, p0[r + 2], p0[r + 3]); mxa = max3f(mxa, p1[r], p1[r + 1]); mxb = max3f(mxb, p1[r + 2], p1[r + 3]); }
;         float mx = fmaxf(mxa, mxb);
;         if (__any(mx > 8.f)) {
.LBB0_578:
	ds_read_b128 v[82:85], v175
	ds_read_b128 v[152:155], v175 offset:32
	ds_read_b128 v[156:159], v175 offset:4608
	ds_read_b128 v[160:163], v175 offset:4640
	v_cvt_f32_u32_e32 v150, v173
	s_waitcnt lgkmcnt(3)
	v_mfma_f32_32x32x16_bf16 v[98:113], v[82:85], v[114:117], v[66:81]
	v_sub_f32_e32 v178, v172, v150
	v_add_f32_e32 v179, -1.0, v178
	s_waitcnt lgkmcnt(1)
	v_mfma_f32_32x32x16_bf16 v[82:97], v[156:159], v[114:117], v[66:81]
	v_mfma_f32_32x32x16_bf16 v[98:113], v[152:155], v[118:121], v[98:113]
	ds_read_b128 v[152:155], v175 offset:64
	ds_read_b128 v[156:159], v175 offset:96
	s_waitcnt lgkmcnt(2)
	v_mfma_f32_32x32x16_bf16 v[82:97], v[160:163], v[118:121], v[82:97]
	s_waitcnt lgkmcnt(1)
	v_mfma_f32_32x32x16_bf16 v[98:113], v[152:155], v[122:125], v[98:113]
	ds_read_b128 v[152:155], v175 offset:4672
	ds_read_b128 v[160:163], v175 offset:4704
	s_waitcnt lgkmcnt(1)
	v_mfma_f32_32x32x16_bf16 v[82:97], v[152:155], v[122:125], v[82:97]
	v_and_b32_e32 v152, 0x7fffffff, v178
	v_and_b32_e32 v153, 0x7fffffff, v179
	v_mfma_f32_32x32x16_bf16 v[98:113], v[156:159], v[126:129], v[98:113]
	s_waitcnt lgkmcnt(0)
	v_mfma_f32_32x32x16_bf16 v[82:97], v[160:163], v[126:129], v[82:97]
	s_nop 15
	s_nop 7
	s_nop 9
	v_pk_fma_f32 v[156:157], v[142:143], v[152:153], v[98:99] neg_lo:[1,0,0] neg_hi:[1,0,0]
	v_pk_add_f32 v[98:99], v[178:179], s[8:9] op_sel_hi:[1,0]
	s_nop 0
	v_fma_f32 v99, -v143, |v99|, v83
	v_fma_f32 v98, -v142, |v98|, v82
	v_pk_add_f32 v[82:83], v[178:179], s[10:11] op_sel_hi:[0,1]
	v_fma_f32 v161, -v143, |v83|, v101
	v_fma_f32 v160, -v142, |v82|, v100
	v_pk_add_f32 v[82:83], v[82:83], s[8:9] op_sel_hi:[1,0]
	v_fma_f32 v153, -v143, |v83|, v85
	v_fma_f32 v152, -v142, |v82|, v84
	v_pk_add_f32 v[82:83], v[178:179], s[22:23] op_sel_hi:[0,1]
	v_fma_f32 v165, -v143, |v83|, v103
	v_fma_f32 v164, -v142, |v82|, v102
	v_pk_add_f32 v[82:83], v[82:83], s[8:9] op_sel_hi:[1,0]
	v_fma_f32 v103, -v143, |v83|, v87
	v_fma_f32 v102, -v142, |v82|, v86
	v_pk_add_f32 v[82:83], v[178:179], s[34:35] op_sel_hi:[0,1]
	v_fma_f32 v167, -v143, |v83|, v105
	v_fma_f32 v166, -v142, |v82|, v104
	v_pk_add_f32 v[82:83], v[82:83], s[8:9] op_sel_hi:[1,0]
	v_fma_f32 v155, -v143, |v83|, v89
	v_fma_f32 v154, -v142, |v82|, v88
	v_pk_add_f32 v[82:83], v[178:179], s[36:37] op_sel_hi:[0,1]
	v_fma_f32 v159, -v143, |v83|, v107
	v_fma_f32 v158, -v142, |v82|, v106
	v_pk_add_f32 v[82:83], v[82:83], s[8:9] op_sel_hi:[1,0]
	v_fma_f32 v101, -v143, |v83|, v91
	v_fma_f32 v100, -v142, |v82|, v90
	v_pk_add_f32 v[82:83], v[178:179], s[38:39] op_sel_hi:[0,1]
	v_fma_f32 v163, -v143, |v83|, v109
	v_fma_f32 v162, -v142, |v82|, v108
	v_pk_add_f32 v[82:83], v[82:83], s[8:9] op_sel_hi:[1,0]
	v_fma_f32 v105, -v143, |v83|, v93
	v_fma_f32 v104, -v142, |v82|, v92
	v_pk_add_f32 v[82:83], v[178:179], s[40:41] op_sel_hi:[0,1]
	v_fma_f32 v111, -v143, |v83|, v111
	v_fma_f32 v110, -v142, |v82|, v110
	v_pk_add_f32 v[82:83], v[82:83], s[8:9] op_sel_hi:[1,0]
	v_fma_f32 v107, -v143, |v83|, v95
	v_fma_f32 v106, -v142, |v82|, v94
	v_pk_add_f32 v[82:83], v[178:179], s[42:43] op_sel_hi:[0,1]
	v_fma_f32 v113, -v143, |v83|, v113
	v_fma_f32 v112, -v142, |v82|, v112
	v_pk_add_f32 v[82:83], v[82:83], s[8:9] op_sel_hi:[1,0]
	v_fma_f32 v109, -v143, |v83|, v97
	v_fma_f32 v108, -v142, |v82|, v96
	v_max3_f32 v82, v156, v157, v98
	v_max3_f32 v83, v160, v161, v99
	v_max3_f32 v82, v82, v152, v153
	v_max3_f32 v83, v83, v166, v167
	v_max3_f32 v82, v82, v164, v165
	v_max3_f32 v83, v83, v154, v155
	v_max3_f32 v82, v82, v102, v103
	v_max3_f32 v83, v83, v162, v163
	v_max3_f32 v82, v82, v158, v159
	v_max3_f32 v83, v83, v104, v105
	v_max3_f32 v82, v82, v100, v101
	v_max3_f32 v83, v83, v112, v113
	v_max3_f32 v82, v82, v110, v111
	v_max3_f32 v83, v83, v108, v109
	v_max3_f32 v82, v82, v106, v107
	v_max_f32_e32 v83, v83, v83
	v_max_f32_e32 v82, v82, v82
	v_max_f32_e32 v82, v82, v83
	v_cmp_gt_f32_e32 vcc, 0xc3400000, v82
	s_cmp_eq_u64 vcc, exec
	s_cbranch_scc1 .Lsk1_p4a1
	v_cmp_lt_f32_e32 vcc, s52, v82
	s_cbranch_vccz .LBB0_580
	v_and_b32_e32 v67, 64, v170
	v_xor_b32_e32 v66, 32, v170
	v_add_u32_e32 v67, 64, v67
	v_cmp_lt_i32_e32 vcc, v66, v67
	s_nop 1
	v_cndmask_b32_e32 v66, v170, v66, vcc
	v_lshlrev_b32_e32 v66, 2, v66
	ds_bpermute_b32 v66, v66, v82
	s_waitcnt lgkmcnt(0)
; #define LAS __attribute__((address_space(3)))
; __device__ __forceinline__ unsigned cvtpk(float lo, float hi) { typedef __bf16 bf2 __attribute__((ext_vector_type(2))); f32x2 v = {lo, hi}; bf2 b = __builtin_convertvector(v, bf2); return __builtin_bit_cast(unsigned, b); }
; template <int DQK, int DV, bool BIAS> ...
;     ...
;         if (__any(mx > 8.f)) {
;             mx = fmaxf(mx, __shfl_xor(mx, 32));
;             const float dl = fmaxf(mx, 0.f); mhat += dl;
;             const float f = __builtin_amdgcn_exp2f(-dl);
; #pragma unroll
;             for (int r = 0; r < 16; ++r) { p0[r] -= dl; p1[r] -= dl; negm[r] = -mhat; }
;             l *= f;
; #pragma unroll
;             for (int d = 0; d < NDT; ++d)
; #pragma unroll
;                 for (int r = 0; r < 16; ++r) o[d][r] *= f;
;         }
;         if (!isY) {
;             const LAS unsigned char* vbase = lds + VOFF + vcur * VBUF + (4 * hi + ((lane & 15) >> 2)) * 64 + ((lane >> 4) & 1) * 32 + (lane & 3) * 8;
;             float ls = 0.f;
; #pragma unroll
;             for (int hs = 0; hs < 4; ++hs) {
;                 float e[8];
; #pragma unroll
;                 for (int j = 0; j < 8; ++j) { e[j] = __builtin_amdgcn_exp2f(hs < 2 ? p0[8 * (hs & 1) + j] : p1[8 * (hs & 1) + j]); ls += e[j]; }
;                 pw[hs].x = cvtpk(e[0], e[1]); pw[hs].y = cvtpk(e[2], e[3]); pw[hs].z = cvtpk(e[4], e[5]); pw[hs].w = cvtpk(e[6], e[7]);
;                 const bf16x8 pbv = __builtin_bit_cast(bf16x8, pw[hs]);
; #pragma unroll
;                 for (int d = 0; d < NDT; ++d) { const LAS unsigned char* vp = vbase + d * 4096 + hs * 1024;
;                     const v4i16_t a0 = __builtin_amdgcn_ds_read_tr16_b64_v4i16((LAS v4i16_t*)vp), a1 = __builtin_amdgcn_ds_read_tr16_b64_v4i16((LAS v4i16_t*)(vp + 512));
;                     const bf16x8 av = {a0[0], a0[1], a0[2], a0[3], a1[0], a1[1], a1[2], a1[3]};
;                     o[d] = __builtin_amdgcn_mfma_f32_32x32x16_bf16(av, pbv, o[d], 0, 0, 0); }
	v_max3_f32 v67, v82, v66, 0
	v_exp_f32_e64 v66, -v67
	v_add_f32_e32 v176, v176, v67
	v_xor_b32_e32 v82, 0x80000000, v176
	v_sub_f32_e32 v98, v98, v67
	v_sub_f32_e32 v99, v99, v67
	v_sub_f32_e32 v152, v152, v67
	v_sub_f32_e32 v153, v153, v67
	v_sub_f32_e32 v102, v102, v67
	v_sub_f32_e32 v103, v103, v67
	v_sub_f32_e32 v154, v154, v67
	v_sub_f32_e32 v155, v155, v67
	v_sub_f32_e32 v100, v100, v67
	v_sub_f32_e32 v101, v101, v67
	v_sub_f32_e32 v104, v104, v67
	v_sub_f32_e32 v105, v105, v67
	v_sub_f32_e32 v106, v106, v67
	v_sub_f32_e32 v107, v107, v67
	v_sub_f32_e32 v108, v108, v67
	v_sub_f32_e32 v109, v109, v67
	v_pk_mul_f32 v[64:65], v[64:65], v[66:67] op_sel_hi:[1,0]
	v_pk_mul_f32 v[62:63], v[62:63], v[66:67] op_sel_hi:[1,0]
	v_pk_mul_f32 v[60:61], v[60:61], v[66:67] op_sel_hi:[1,0]
	v_pk_mul_f32 v[58:59], v[58:59], v[66:67] op_sel_hi:[1,0]
	v_pk_mul_f32 v[56:57], v[56:57], v[66:67] op_sel_hi:[1,0]
	v_pk_mul_f32 v[54:55], v[54:55], v[66:67] op_sel_hi:[1,0]
	v_pk_mul_f32 v[52:53], v[52:53], v[66:67] op_sel_hi:[1,0]
	v_pk_mul_f32 v[50:51], v[50:51], v[66:67] op_sel_hi:[1,0]
	v_pk_mul_f32 v[48:49], v[48:49], v[66:67] op_sel_hi:[1,0]
	v_pk_mul_f32 v[46:47], v[46:47], v[66:67] op_sel_hi:[1,0]
	v_pk_mul_f32 v[44:45], v[44:45], v[66:67] op_sel_hi:[1,0]
	v_pk_mul_f32 v[42:43], v[42:43], v[66:67] op_sel_hi:[1,0]
	v_pk_mul_f32 v[40:41], v[40:41], v[66:67] op_sel_hi:[1,0]
	v_pk_mul_f32 v[38:39], v[38:39], v[66:67] op_sel_hi:[1,0]
	v_pk_mul_f32 v[36:37], v[36:37], v[66:67] op_sel_hi:[1,0]
	v_pk_mul_f32 v[34:35], v[34:35], v[66:67] op_sel_hi:[1,0]
	v_pk_mul_f32 v[32:33], v[32:33], v[66:67] op_sel_hi:[1,0]
	v_pk_mul_f32 v[30:31], v[30:31], v[66:67] op_sel_hi:[1,0]
	v_pk_mul_f32 v[28:29], v[28:29], v[66:67] op_sel_hi:[1,0]
	v_pk_mul_f32 v[26:27], v[26:27], v[66:67] op_sel_hi:[1,0]
	v_pk_mul_f32 v[24:25], v[24:25], v[66:67] op_sel_hi:[1,0]
	v_pk_mul_f32 v[22:23], v[22:23], v[66:67] op_sel_hi:[1,0]
	v_pk_mul_f32 v[20:21], v[20:21], v[66:67] op_sel_hi:[1,0]
	v_pk_mul_f32 v[18:19], v[18:19], v[66:67] op_sel_hi:[1,0]
	v_pk_mul_f32 v[16:17], v[16:17], v[66:67] op_sel_hi:[1,0]
	v_pk_mul_f32 v[14:15], v[14:15], v[66:67] op_sel_hi:[1,0]
	v_pk_mul_f32 v[12:13], v[12:13], v[66:67] op_sel_hi:[1,0]
	v_pk_mul_f32 v[10:11], v[10:11], v[66:67] op_sel_hi:[1,0]
	v_pk_mul_f32 v[8:9], v[8:9], v[66:67] op_sel_hi:[1,0]
	v_pk_mul_f32 v[6:7], v[6:7], v[66:67] op_sel_hi:[1,0]
	v_pk_mul_f32 v[4:5], v[4:5], v[66:67] op_sel_hi:[1,0]
	v_pk_mul_f32 v[2:3], v[2:3], v[66:67] op_sel_hi:[1,0]
	v_sub_f32_e32 v156, v156, v67
	v_sub_f32_e32 v157, v157, v67
	v_sub_f32_e32 v160, v160, v67
	v_sub_f32_e32 v161, v161, v67
	v_sub_f32_e32 v164, v164, v67
	v_sub_f32_e32 v165, v165, v67
	v_sub_f32_e32 v166, v166, v67
	v_sub_f32_e32 v167, v167, v67
	v_sub_f32_e32 v158, v158, v67
	v_sub_f32_e32 v159, v159, v67
	v_sub_f32_e32 v162, v162, v67
	v_sub_f32_e32 v163, v163, v67
	v_sub_f32_e32 v110, v110, v67
	v_sub_f32_e32 v111, v111, v67
	v_sub_f32_e32 v112, v112, v67
	v_sub_f32_e32 v113, v113, v67
	v_mul_f32_e32 v151, v151, v66
	v_mov_b32_e32 v66, v82
	v_mov_b32_e32 v67, v82
	v_mov_b32_e32 v68, v82
	v_mov_b32_e32 v69, v82
	v_mov_b32_e32 v70, v82
	v_mov_b32_e32 v71, v82
	v_mov_b32_e32 v72, v82
	v_mov_b32_e32 v73, v82
	v_mov_b32_e32 v74, v82
	v_mov_b32_e32 v75, v82
	v_mov_b32_e32 v76, v82
	v_mov_b32_e32 v77, v82
	v_mov_b32_e32 v78, v82
	v_mov_b32_e32 v79, v82
	v_mov_b32_e32 v80, v82
	v_mov_b32_e32 v81, v82
	s_branch .LBB0_581
.Lsk1_p4a1:
	v_mov_b32_e32 v150, 0
	v_mov_b32_e32 v152, 0
	v_mov_b32_e32 v153, 0
	v_mov_b32_e32 v154, 0
	v_mov_b32_e32 v155, 0
	v_mov_b32_e32 v156, 0
	v_mov_b32_e32 v157, 0
	v_mov_b32_e32 v158, 0
	v_mov_b32_e32 v159, 0
	v_mov_b32_e32 v160, 0
	v_mov_b32_e32 v161, 0
	v_mov_b32_e32 v162, 0
	v_mov_b32_e32 v163, 0
	v_mov_b32_e32 v164, 0
	v_mov_b32_e32 v165, 0
	v_mov_b32_e32 v166, 0
	v_mov_b32_e32 v167, 0
	v_mov_b32_e32 v177, 0
	v_mov_b32_e32 v178, 0
	v_mov_b32_e32 v179, 0
	v_mov_b32_e32 v180, 0
	v_mov_b32_e32 v181, 0
	v_mov_b32_e32 v182, 0
	v_mov_b32_e32 v183, 0
	v_mov_b32_e32 v184, 0
	v_mov_b32_e32 v185, 0
	v_mov_b32_e32 v186, 0
	v_mov_b32_e32 v187, 0
	v_mov_b32_e32 v188, 0
	v_mov_b32_e32 v189, 0
	v_mov_b32_e32 v190, 0
	v_mov_b32_e32 v191, 0
	s_branch .Lend1_p4a1
.LBB0_580:
.LBB0_581:
	v_exp_f32_e32 v156, v156
	v_exp_f32_e32 v157, v157
	v_exp_f32_e32 v160, v160
	v_exp_f32_e32 v161, v161
	v_exp_f32_e32 v164, v164
	v_exp_f32_e32 v150, v165
	ds_read_b64_tr_b16 v[178:179], v174 offset:18432
	ds_read_b64_tr_b16 v[180:181], v174 offset:18944
	v_exp_f32_e32 v165, v166
	v_exp_f32_e32 v166, v167
	ds_read_b64_tr_b16 v[186:187], v174 offset:22528
	ds_read_b64_tr_b16 v[188:189], v174 offset:23040
	v_cvt_pk_bf16_f32 v182, v156, v157
	v_cvt_pk_bf16_f32 v183, v160, v161
	v_cvt_pk_bf16_f32 v184, v164, v150
	v_cvt_pk_bf16_f32 v185, v165, v166
	s_waitcnt lgkmcnt(2)
	s_nop 0
	v_mfma_f32_32x32x16_bf16 v[50:65], v[178:181], v[182:185], v[50:65]
	s_waitcnt lgkmcnt(0)
	v_mfma_f32_32x32x16_bf16 v[34:49], v[186:189], v[182:185], v[34:49]
	ds_read_b64_tr_b16 v[178:179], v174 offset:26624
	ds_read_b64_tr_b16 v[180:181], v174 offset:27136
	ds_read_b64_tr_b16 v[186:187], v174 offset:30720
	ds_read_b64_tr_b16 v[188:189], v174 offset:31232
	s_waitcnt lgkmcnt(2)
	v_mfma_f32_32x32x16_bf16 v[18:33], v[178:181], v[182:185], v[18:33]
	s_waitcnt lgkmcnt(0)
	v_mfma_f32_32x32x16_bf16 v[2:17], v[186:189], v[182:185], v[2:17]
	v_exp_f32_e32 v167, v158
	v_exp_f32_e32 v177, v159
	v_exp_f32_e32 v178, v162
	v_exp_f32_e32 v158, v163
	v_exp_f32_e32 v159, v110
	v_exp_f32_e32 v162, v111
	ds_read_b64_tr_b16 v[180:181], v174 offset:19456
	ds_read_b64_tr_b16 v[182:183], v174 offset:19968
	v_exp_f32_e32 v163, v112
	v_exp_f32_e32 v179, v113
	ds_read_b64_tr_b16 v[184:185], v174 offset:23552
	ds_read_b64_tr_b16 v[186:187], v174 offset:24064
	v_cvt_pk_bf16_f32 v110, v167, v177
	v_cvt_pk_bf16_f32 v111, v178, v158
	v_cvt_pk_bf16_f32 v112, v159, v162
	v_cvt_pk_bf16_f32 v113, v163, v179
	s_waitcnt lgkmcnt(2)
; #define LAS __attribute__((address_space(3)))
; __device__ __forceinline__ unsigned cvtpk(float lo, float hi) { typedef __bf16 bf2 __attribute__((ext_vector_type(2))); f32x2 v = {lo, hi}; bf2 b = __builtin_convertvector(v, bf2); return __builtin_bit_cast(unsigned, b); }
; template <int DQK, int DV, bool BIAS> ...
;     ...
;         __syncthreads();
;         if (g + 1 < NG) {
; #pragma unroll
;             for (int j = 0; j < TPB; ++j) ATT_STORE((pair ^ 1) * TPB + j, j);
;             if (g + 2 < NG) {
; #pragma unroll
;                 for (int j = 0; j < TPB; ++j) ATT_LOAD((g + 2) * TPB + j, j);
;             }
;         }
; #pragma unroll
;       for (int sub = 0; sub < TPB; ++sub) {
;         const int t = g * TPB + sub, buf = pair * TPB + sub, vcur = buf;
;         f32x16 p0, p1;
;         const LAS unsigned char* kb = lds + buf * KBUF + r32 * KP + hi * 16;
; #pragma unroll
;         for (int ks = 0; ks < NKS; ++ks) {
;             const bf16x8 k0 = *(const LAS bf16x8*)(kb + ks * 32), k1 = *(const LAS bf16x8*)(kb + 32 * KP + ks * 32);
;             if (ks == 0) { p0 = __builtin_amdgcn_mfma_f32_32x32x16_bf16(k0, qf[0], negm, 0, 0, 0); p1 = __builtin_amdgcn_mfma_f32_32x32x16_bf16(k1, qf[0], negm, 0, 0, 0); }
;             else { p0 = __builtin_amdgcn_mfma_f32_32x32x16_bf16(k0, qf[ks], p0, 0, 0, 0); p1 = __builtin_amdgcn_mfma_f32_32x32x16_bf16(k1, qf[ks], p1, 0, 0, 0); }
;         }
;     ...
;                 for (int j = 0; j < 8; ++j) { e[j] = __builtin_amdgcn_exp2f(hs < 2 ? p0[8 * (hs & 1) + j] : p1[8 * (hs & 1) + j]); ls += e[j]; }
;                 pw[hs].x = cvtpk(e[0], e[1]); pw[hs].y = cvtpk(e[2], e[3]); pw[hs].z = cvtpk(e[4], e[5]); pw[hs].w = cvtpk(e[6], e[7]);
;                 const bf16x8 pbv = __builtin_bit_cast(bf16x8, pw[hs]);
; #pragma unroll
;                 for (int d = 0; d < NDT; ++d) { const LAS unsigned char* vp = vbase + d * 4096 + hs * 1024;
;                     const v4i16_t a0 = __builtin_amdgcn_ds_read_tr16_b64_v4i16((LAS v4i16_t*)vp), a1 = __builtin_amdgcn_ds_read_tr16_b64_v4i16((LAS v4i16_t*)(vp + 512));
;                     const bf16x8 av = {a0[0], a0[1], a0[2], a0[3], a1[0], a1[1], a1[2], a1[3]};
;                     o[d] = __builtin_amdgcn_mfma_f32_32x32x16_bf16(av, pbv, o[d], 0, 0, 0); }
;                 __builtin_amdgcn_sched_barrier(0);
;             }
;             l += ls;
	s_nop 0
	v_mfma_f32_32x32x16_bf16 v[50:65], v[180:183], v[110:113], v[50:65]
	s_waitcnt lgkmcnt(0)
	v_mfma_f32_32x32x16_bf16 v[34:49], v[184:187], v[110:113], v[34:49]
	ds_read_b64_tr_b16 v[180:181], v174 offset:27648
	ds_read_b64_tr_b16 v[182:183], v174 offset:28160
	ds_read_b64_tr_b16 v[184:185], v174 offset:31744
	ds_read_b64_tr_b16 v[186:187], v174 offset:32256
	s_waitcnt lgkmcnt(2)
	v_mfma_f32_32x32x16_bf16 v[18:33], v[180:183], v[110:113], v[18:33]
	s_waitcnt lgkmcnt(0)
	v_mfma_f32_32x32x16_bf16 v[2:17], v[184:187], v[110:113], v[2:17]
	v_exp_f32_e32 v180, v98
	v_exp_f32_e32 v181, v99
	v_exp_f32_e32 v152, v152
	v_exp_f32_e32 v153, v153
	v_exp_f32_e32 v182, v102
	ds_read_b64_tr_b16 v[110:111], v174 offset:20480
	ds_read_b64_tr_b16 v[112:113], v174 offset:20992
	v_exp_f32_e32 v183, v103
	v_exp_f32_e32 v154, v154
	v_exp_f32_e32 v155, v155
	v_cvt_pk_bf16_f32 v184, v180, v181
	v_cvt_pk_bf16_f32 v185, v152, v153
	v_cvt_pk_bf16_f32 v186, v182, v183
	v_cvt_pk_bf16_f32 v187, v154, v155
	ds_read_b64_tr_b16 v[190:191], v174 offset:33280
	s_waitcnt lgkmcnt(1)
	v_mfma_f32_32x32x16_bf16 v[50:65], v[110:113], v[184:187], v[50:65]
	ds_read_b64_tr_b16 v[110:111], v174 offset:24576
	ds_read_b64_tr_b16 v[112:113], v174 offset:25088
	ds_read_b64_tr_b16 v[192:193], v174 offset:28672
	ds_read_b64_tr_b16 v[194:195], v174 offset:29184
	ds_read_b64_tr_b16 v[188:189], v174 offset:32768
	s_waitcnt lgkmcnt(3)
	v_mfma_f32_32x32x16_bf16 v[34:49], v[110:113], v[184:187], v[34:49]
	s_waitcnt lgkmcnt(1)
	v_mfma_f32_32x32x16_bf16 v[18:33], v[192:195], v[184:187], v[18:33]
	s_waitcnt lgkmcnt(0)
	v_mfma_f32_32x32x16_bf16 v[2:17], v[188:191], v[184:187], v[2:17]
	v_exp_f32_e32 v184, v100
	v_exp_f32_e32 v185, v101
	v_exp_f32_e32 v186, v104
	v_exp_f32_e32 v187, v105
	v_exp_f32_e32 v188, v106
	ds_read_b64_tr_b16 v[98:99], v174 offset:21504
	ds_read_b64_tr_b16 v[100:101], v174 offset:22016
	v_exp_f32_e32 v191, v107
	v_exp_f32_e32 v189, v108
	v_exp_f32_e32 v190, v109
	v_cvt_pk_bf16_f32 v102, v184, v185
	v_cvt_pk_bf16_f32 v103, v186, v187
	v_cvt_pk_bf16_f32 v104, v188, v191
	v_cvt_pk_bf16_f32 v105, v189, v190
	ds_read_b64_tr_b16 v[108:109], v174 offset:34304
	s_waitcnt lgkmcnt(1)
	v_mfma_f32_32x32x16_bf16 v[50:65], v[98:101], v[102:105], v[50:65]
	ds_read_b64_tr_b16 v[98:99], v174 offset:25600
	ds_read_b64_tr_b16 v[100:101], v174 offset:26112
	ds_read_b64_tr_b16 v[110:111], v174 offset:29696
	ds_read_b64_tr_b16 v[112:113], v174 offset:30208
	ds_read_b64_tr_b16 v[106:107], v174 offset:33792
	s_waitcnt lgkmcnt(3)
	v_mfma_f32_32x32x16_bf16 v[34:49], v[98:101], v[102:105], v[34:49]
	s_waitcnt lgkmcnt(1)
	v_mfma_f32_32x32x16_bf16 v[18:33], v[110:113], v[102:105], v[18:33]
	s_waitcnt lgkmcnt(0)
	v_mfma_f32_32x32x16_bf16 v[2:17], v[106:109], v[102:105], v[2:17]
.Lend1_p4a1:
	s_cmp_eq_u32 s6, 0x1876000
	s_barrier
	s_cbranch_scc1 .LBB0_584
	s_andn2_b64 vcc, exec, s[44:45]
	s_waitcnt vmcnt(0)
	ds_write_b128 v168, v[138:141]
	ds_write_b128 v171, v[130:133] offset:18432
	ds_write_b128 v171, v[134:137] offset:26624
	s_cbranch_vccnz .LBB0_584
	v_lshl_add_u64 v[98:99], v[148:149], 0, s[6:7]
	v_add_co_u32_e32 v98, vcc, 0x12f000, v98
	v_lshl_add_u64 v[100:101], v[146:147], 0, s[6:7]
	s_nop 0
	v_addc_co_u32_e32 v99, vcc, 0, v99, vcc
	v_add_co_u32_e32 v100, vcc, 0x12f000, v100
	s_nop 1
	v_addc_co_u32_e32 v101, vcc, 0, v101, vcc
	global_load_dwordx4 v[130:133], v[98:99], off offset:2048
	global_load_dwordx4 v[134:137], v[100:101], off offset:2048
	v_lshl_add_u64 v[98:99], v[144:145], 0, s[6:7]
	v_add_co_u32_e32 v98, vcc, 0x12f000, v98
	s_nop 1
	v_addc_co_u32_e32 v99, vcc, 0, v99, vcc
	global_load_dwordx4 v[138:141], v[98:99], off offset:1024
.LBB0_584:
	ds_read_b128 v[192:195], v175 offset:9216
	ds_read_b128 v[196:199], v175 offset:9248
	v_add_f32_e32 v156, 0, v156
	v_add_f32_e32 v156, v157, v156
	v_add_f32_e32 v156, v160, v156
	s_waitcnt lgkmcnt(1)
	v_mfma_f32_32x32x16_bf16 v[98:113], v[192:195], v[114:117], v[66:81]
	ds_read_b128 v[192:195], v175 offset:13824
	ds_read_b128 v[200:203], v175 offset:13856
	v_add_f32_e32 v156, v161, v156
	v_add_f32_e32 v156, v164, v156
	v_add_f32_e32 v150, v150, v156
	v_add_f32_e32 v150, v165, v150
	v_add_f32_e32 v150, v166, v150
	v_add_f32_e32 v150, v167, v150
	s_waitcnt lgkmcnt(1)
	v_mfma_f32_32x32x16_bf16 v[82:97], v[192:195], v[114:117], v[66:81]
	v_add_f32_e32 v150, v177, v150
	v_add_f32_e32 v150, v178, v150
	v_add_f32_e32 v150, v158, v150
	v_add_f32_e32 v150, v159, v150
	ds_read_b128 v[164:167], v175 offset:9280
	v_add_f32_e32 v150, v162, v150
	v_add_f32_e32 v150, v163, v150
	v_mfma_f32_32x32x16_bf16 v[98:113], v[196:199], v[118:121], v[98:113]
	v_add_f32_e32 v150, v179, v150
	v_add_f32_e32 v150, v180, v150
	v_add_f32_e32 v150, v181, v150
	v_add_f32_e32 v150, v152, v150
	ds_read_b128 v[156:159], v175 offset:13888
	ds_read_b128 v[160:163], v175 offset:9312
	v_add_f32_e32 v150, v153, v150
	v_add_f32_e32 v150, v182, v150
	s_waitcnt lgkmcnt(3)
	v_mfma_f32_32x32x16_bf16 v[82:97], v[200:203], v[118:121], v[82:97]
	v_add_f32_e32 v150, v183, v150
	v_add_f32_e32 v150, v154, v150
	v_add_f32_e32 v150, v155, v150
	v_add_f32_e32 v150, v184, v150
	v_add_f32_e32 v150, v185, v150
	v_add_u32_e32 v152, 64, v173
	v_add_f32_e32 v150, v186, v150
	s_waitcnt lgkmcnt(2)
	v_mfma_f32_32x32x16_bf16 v[98:113], v[164:167], v[122:125], v[98:113]
	ds_read_b128 v[164:167], v175 offset:13920
	v_cvt_f32_u32_e32 v152, v152
	v_add_f32_e32 v150, v187, v150
	v_add_f32_e32 v150, v188, v150
	v_add_f32_e32 v150, v191, v150
	v_add_f32_e32 v150, v189, v150
	v_add_f32_e32 v150, v190, v150
	s_waitcnt lgkmcnt(2)
	v_mfma_f32_32x32x16_bf16 v[82:97], v[156:159], v[122:125], v[82:97]
	v_add_f32_e32 v158, v151, v150
	s_waitcnt lgkmcnt(1)
; __device__ __forceinline__ float max3f(float a, float b, float c) { float r; asm("v_max3_f32 %0, %1, %2, %3" : "=v"(r) : "v"(a), "v"(b), "v"(c)); return r; }
; template <int DQK, int DV, bool BIAS> ...
;     ...
;         if (BIAS) {
;             asm volatile("s_nop 15\n\ts_nop 7" : "+v"(p0), "+v"(p1));
;             const float d0 = qp - (float)(t * 64 + 4 * hi);
; #pragma unroll
;             for (int r = 0; r < 16; ++r) { const float dk = d0 - (float)((r & 3) + 8 * (r >> 2)); p0[r] = p0[r] - sl2 * fabsf(dk); p1[r] = p1[r] - sl2 * fabsf(dk - 32.f); }
;         } else {
;             asm volatile("s_nop 15\n\ts_nop 7" : "+v"(p0), "+v"(p1));
;         }
;         float mxa = max3f(p0[0], p0[1], p1[0]), mxb = max3f(p0[2], p0[3], p1[1]); mxa = max3f(mxa, p1[2], p1[3]);
; #pragma unroll
;         for (int r = 4; r < 16; r += 4) { mxa = max3f(mxa, p0[r], p0[r + 1]); mxb = max3f(mxb, p0[r + 2], p0[r + 3]); mxa = max3f(mxa, p1[r], p1[r + 1]); mxb = max3f(mxb, p1[r + 2], p1[r + 3]); }
;         float mx = fmaxf(mxa, mxb);
;         if (__any(mx > 8.f)) {
;             mx = fmaxf(mx, __shfl_xor(mx, 32));
;             const float dl = fmaxf(mx, 0.f); mhat += dl;
;             const float f = __builtin_amdgcn_exp2f(-dl);
; #pragma unroll
;             for (int r = 0; r < 16; ++r) { p0[r] -= dl; p1[r] -= dl; negm[r] = -mhat; }
;             l *= f;
; #pragma unroll
;             for (int d = 0; d < NDT; ++d)
; #pragma unroll
;                 for (int r = 0; r < 16; ++r) o[d][r] *= f;
;         }
	v_mfma_f32_32x32x16_bf16 v[98:113], v[160:163], v[126:129], v[98:113]
	v_sub_f32_e32 v160, v172, v152
	v_add_f32_e32 v161, -1.0, v160
	v_and_b32_e32 v150, 0x7fffffff, v160
	v_and_b32_e32 v151, 0x7fffffff, v161
	s_waitcnt lgkmcnt(0)
	v_mfma_f32_32x32x16_bf16 v[82:97], v[164:167], v[126:129], v[82:97]
	s_nop 15
	s_nop 7
	s_nop 5
	v_pk_fma_f32 v[150:151], v[142:143], v[150:151], v[98:99] neg_lo:[1,0,0] neg_hi:[1,0,0]
	v_pk_add_f32 v[98:99], v[160:161], s[8:9] op_sel_hi:[1,0]
	s_nop 0
	v_fma_f32 v83, -v143, |v99|, v83
	v_fma_f32 v82, -v142, |v98|, v82
	s_nop 0
	v_pk_add_f32 v[98:99], v[160:161], s[10:11] op_sel_hi:[0,1]
	v_fma_f32 v153, -v143, |v99|, v101
	v_fma_f32 v152, -v142, |v98|, v100
	v_pk_add_f32 v[98:99], v[98:99], s[8:9] op_sel_hi:[1,0]
	v_fma_f32 v99, -v143, |v99|, v85
	v_fma_f32 v98, -v142, |v98|, v84
	v_pk_add_f32 v[84:85], v[160:161], s[22:23] op_sel_hi:[0,1]
	v_fma_f32 v155, -v143, |v85|, v103
	v_fma_f32 v154, -v142, |v84|, v102
	v_pk_add_f32 v[84:85], v[84:85], s[8:9] op_sel_hi:[1,0]
	v_fma_f32 v101, -v143, |v85|, v87
	v_fma_f32 v100, -v142, |v84|, v86
	v_pk_add_f32 v[84:85], v[160:161], s[34:35] op_sel_hi:[0,1]
	v_fma_f32 v157, -v143, |v85|, v105
	v_fma_f32 v156, -v142, |v84|, v104
	v_pk_add_f32 v[84:85], v[84:85], s[8:9] op_sel_hi:[1,0]
	v_fma_f32 v103, -v143, |v85|, v89
	v_fma_f32 v102, -v142, |v84|, v88
	v_pk_add_f32 v[84:85], v[160:161], s[36:37] op_sel_hi:[0,1]
	v_fma_f32 v105, -v143, |v85|, v107
	v_fma_f32 v104, -v142, |v84|, v106
	v_pk_add_f32 v[86:87], v[160:161], s[38:39] op_sel_hi:[0,1]
	v_pk_add_f32 v[84:85], v[84:85], s[8:9] op_sel_hi:[1,0]
	v_fma_f32 v107, -v143, |v87|, v109
	v_fma_f32 v106, -v142, |v86|, v108
	v_fma_f32 v85, -v143, |v85|, v91
	v_fma_f32 v84, -v142, |v84|, v90
	v_pk_add_f32 v[86:87], v[86:87], s[8:9] op_sel_hi:[1,0]
	v_pk_add_f32 v[88:89], v[160:161], s[40:41] op_sel_hi:[0,1]
	v_fma_f32 v87, -v143, |v87|, v93
	v_fma_f32 v86, -v142, |v86|, v92
	v_fma_f32 v93, -v143, |v89|, v111
	v_fma_f32 v92, -v142, |v88|, v110
	v_pk_add_f32 v[88:89], v[88:89], s[8:9] op_sel_hi:[1,0]
	v_fma_f32 v89, -v143, |v89|, v95
	v_fma_f32 v88, -v142, |v88|, v94
	v_pk_add_f32 v[90:91], v[160:161], s[42:43] op_sel_hi:[0,1]
	v_fma_f32 v95, -v143, |v91|, v113
	v_fma_f32 v94, -v142, |v90|, v112
	v_pk_add_f32 v[90:91], v[90:91], s[8:9] op_sel_hi:[1,0]
	v_fma_f32 v91, -v143, |v91|, v97
	v_fma_f32 v90, -v142, |v90|, v96
	v_max3_f32 v96, v150, v151, v82
	v_max3_f32 v97, v152, v153, v83
	v_max3_f32 v96, v96, v98, v99
	v_max3_f32 v97, v97, v156, v157
	v_max3_f32 v96, v96, v154, v155
	v_max3_f32 v97, v97, v102, v103
	v_max3_f32 v96, v96, v100, v101
	v_max3_f32 v97, v97, v106, v107
	v_max3_f32 v96, v96, v104, v105
	v_max3_f32 v97, v97, v86, v87
	v_max3_f32 v96, v96, v84, v85
	v_max3_f32 v97, v97, v94, v95
	v_max3_f32 v96, v96, v92, v93
	v_max3_f32 v97, v97, v90, v91
	v_max3_f32 v96, v96, v88, v89
	v_max_f32_e32 v97, v97, v97
	v_max_f32_e32 v96, v96, v96
	v_max_f32_e32 v96, v96, v97
	v_cmp_gt_f32_e32 vcc, 0xc3400000, v96
	s_cmp_eq_u64 vcc, exec
	s_cbranch_scc1 .Lsk2_p4a1
	v_cmp_lt_f32_e32 vcc, s52, v96
	s_cbranch_vccz .LBB0_575
	v_and_b32_e32 v67, 64, v170
	v_xor_b32_e32 v66, 32, v170
	v_add_u32_e32 v67, 64, v67
	v_cmp_lt_i32_e32 vcc, v66, v67
	s_nop 1
	v_cndmask_b32_e32 v66, v170, v66, vcc
	v_lshlrev_b32_e32 v66, 2, v66
	ds_bpermute_b32 v66, v66, v96
	s_waitcnt lgkmcnt(0)
	v_max3_f32 v67, v96, v66, 0
	v_exp_f32_e64 v68, -v67
	v_add_f32_e32 v176, v176, v67
	v_xor_b32_e32 v66, 0x80000000, v176
	v_sub_f32_e32 v82, v82, v67
	v_sub_f32_e32 v83, v83, v67
	v_sub_f32_e32 v98, v98, v67
	v_sub_f32_e32 v99, v99, v67
	v_sub_f32_e32 v100, v100, v67
	v_sub_f32_e32 v101, v101, v67
	v_sub_f32_e32 v102, v102, v67
	v_sub_f32_e32 v103, v103, v67
	v_sub_f32_e32 v84, v84, v67
	v_sub_f32_e32 v85, v85, v67
	v_sub_f32_e32 v86, v86, v67
	v_sub_f32_e32 v87, v87, v67
	v_sub_f32_e32 v88, v88, v67
	v_sub_f32_e32 v89, v89, v67
	v_sub_f32_e32 v90, v90, v67
	v_sub_f32_e32 v91, v91, v67
	v_pk_mul_f32 v[64:65], v[64:65], v[68:69] op_sel_hi:[1,0]
	v_pk_mul_f32 v[62:63], v[62:63], v[68:69] op_sel_hi:[1,0]
	v_pk_mul_f32 v[60:61], v[60:61], v[68:69] op_sel_hi:[1,0]
	v_pk_mul_f32 v[58:59], v[58:59], v[68:69] op_sel_hi:[1,0]
	v_pk_mul_f32 v[56:57], v[56:57], v[68:69] op_sel_hi:[1,0]
	v_pk_mul_f32 v[54:55], v[54:55], v[68:69] op_sel_hi:[1,0]
	v_pk_mul_f32 v[52:53], v[52:53], v[68:69] op_sel_hi:[1,0]
	v_pk_mul_f32 v[50:51], v[50:51], v[68:69] op_sel_hi:[1,0]
	v_pk_mul_f32 v[48:49], v[48:49], v[68:69] op_sel_hi:[1,0]
	v_pk_mul_f32 v[46:47], v[46:47], v[68:69] op_sel_hi:[1,0]
	v_pk_mul_f32 v[44:45], v[44:45], v[68:69] op_sel_hi:[1,0]
	v_pk_mul_f32 v[42:43], v[42:43], v[68:69] op_sel_hi:[1,0]
	v_pk_mul_f32 v[40:41], v[40:41], v[68:69] op_sel_hi:[1,0]
	v_pk_mul_f32 v[38:39], v[38:39], v[68:69] op_sel_hi:[1,0]
	v_pk_mul_f32 v[36:37], v[36:37], v[68:69] op_sel_hi:[1,0]
	v_pk_mul_f32 v[34:35], v[34:35], v[68:69] op_sel_hi:[1,0]
	v_pk_mul_f32 v[32:33], v[32:33], v[68:69] op_sel_hi:[1,0]
	v_pk_mul_f32 v[30:31], v[30:31], v[68:69] op_sel_hi:[1,0]
	v_pk_mul_f32 v[28:29], v[28:29], v[68:69] op_sel_hi:[1,0]
	v_pk_mul_f32 v[26:27], v[26:27], v[68:69] op_sel_hi:[1,0]
	v_pk_mul_f32 v[24:25], v[24:25], v[68:69] op_sel_hi:[1,0]
	v_pk_mul_f32 v[22:23], v[22:23], v[68:69] op_sel_hi:[1,0]
	v_pk_mul_f32 v[20:21], v[20:21], v[68:69] op_sel_hi:[1,0]
	v_pk_mul_f32 v[18:19], v[18:19], v[68:69] op_sel_hi:[1,0]
	v_pk_mul_f32 v[16:17], v[16:17], v[68:69] op_sel_hi:[1,0]
	v_pk_mul_f32 v[14:15], v[14:15], v[68:69] op_sel_hi:[1,0]
	v_pk_mul_f32 v[12:13], v[12:13], v[68:69] op_sel_hi:[1,0]
	v_pk_mul_f32 v[10:11], v[10:11], v[68:69] op_sel_hi:[1,0]
	v_pk_mul_f32 v[8:9], v[8:9], v[68:69] op_sel_hi:[1,0]
	v_pk_mul_f32 v[6:7], v[6:7], v[68:69] op_sel_hi:[1,0]
	v_pk_mul_f32 v[4:5], v[4:5], v[68:69] op_sel_hi:[1,0]
	v_pk_mul_f32 v[2:3], v[2:3], v[68:69] op_sel_hi:[1,0]
	v_sub_f32_e32 v150, v150, v67
	v_sub_f32_e32 v151, v151, v67
	v_sub_f32_e32 v152, v152, v67
	v_sub_f32_e32 v153, v153, v67
	v_sub_f32_e32 v154, v154, v67
	v_sub_f32_e32 v155, v155, v67
	v_sub_f32_e32 v156, v156, v67
	v_sub_f32_e32 v157, v157, v67
	v_sub_f32_e32 v104, v104, v67
	v_sub_f32_e32 v105, v105, v67
	v_sub_f32_e32 v106, v106, v67
	v_sub_f32_e32 v107, v107, v67
	v_sub_f32_e32 v92, v92, v67
	v_sub_f32_e32 v93, v93, v67
	v_sub_f32_e32 v94, v94, v67
	v_sub_f32_e32 v95, v95, v67
	v_mul_f32_e32 v158, v158, v68
	v_mov_b32_e32 v67, v66
	v_mov_b32_e32 v68, v66
	v_mov_b32_e32 v69, v66
	v_mov_b32_e32 v70, v66
	v_mov_b32_e32 v71, v66
	v_mov_b32_e32 v72, v66
	v_mov_b32_e32 v73, v66
	v_mov_b32_e32 v74, v66
	v_mov_b32_e32 v75, v66
	v_mov_b32_e32 v76, v66
	v_mov_b32_e32 v77, v66
	v_mov_b32_e32 v78, v66
	v_mov_b32_e32 v79, v66
	v_mov_b32_e32 v80, v66
	v_mov_b32_e32 v81, v66
	s_branch .LBB0_575
.Lsk2_p4a1:
	v_mov_b32_e32 v82, 0
	s_branch .Lend2_p4a1

; template <int DQK, int DV, bool BIAS> ...
;     ...
;     for (int g = 0; g < NG; ++g) {
;         const int pair = g & 1;
;         __syncthreads();
;         if (g + 1 < NG) {
;     ...
;             l += ls;
.Lend2_p4a2:
	s_add_u32 s4, s4, 0xca000
	s_addc_u32 s5, s5, 0
	s_add_i32 s7, s7, 2
	v_add_f32_e32 v151, v158, v82
	s_cmp_lg_u32 s4, 0x1940000
	v_add_u32_e32 v177, 0x80, v177
	s_cbranch_scc0 .LBB0_598

; #define LAS __attribute__((address_space(3)))
; __device__ __forceinline__ float max3f(float a, float b, float c) { float r; asm("v_max3_f32 %0, %1, %2, %3" : "=v"(r) : "v"(a), "v"(b), "v"(c)); return r; }
; template <int DQK, int DV, bool BIAS> ...
;     ...
;         const LAS unsigned char* kb = lds + buf * KBUF + r32 * KP + hi * 16;
; #pragma unroll
;         for (int ks = 0; ks < NKS; ++ks) {
;             const bf16x8 k0 = *(const LAS bf16x8*)(kb + ks * 32), k1 = *(const LAS bf16x8*)(kb + 32 * KP + ks * 32);
;             if (ks == 0) { p0 = __builtin_amdgcn_mfma_f32_32x32x16_bf16(k0, qf[0], negm, 0, 0, 0); p1 = __builtin_amdgcn_mfma_f32_32x32x16_bf16(k1, qf[0], negm, 0, 0, 0); }
;             else { p0 = __builtin_amdgcn_mfma_f32_32x32x16_bf16(k0, qf[ks], p0, 0, 0, 0); p1 = __builtin_amdgcn_mfma_f32_32x32x16_bf16(k1, qf[ks], p1, 0, 0, 0); }
;         }
;         if (BIAS) {
;             asm volatile("s_nop 15\n\ts_nop 7" : "+v"(p0), "+v"(p1));
;             const float d0 = qp - (float)(t * 64 + 4 * hi);
; #pragma unroll
;             for (int r = 0; r < 16; ++r) { const float dk = d0 - (float)((r & 3) + 8 * (r >> 2)); p0[r] = p0[r] - sl2 * fabsf(dk); p1[r] = p1[r] - sl2 * fabsf(dk - 32.f); }
;         } else {
;             asm volatile("s_nop 15\n\ts_nop 7" : "+v"(p0), "+v"(p1));
;         }
;         float mxa = max3f(p0[0], p0[1], p1[0]), mxb = max3f(p0[2], p0[3], p1[1]); mxa = max3f(mxa, p1[2], p1[3]);
; #pragma unroll
;         for (int r = 4; r < 16; r += 4) { mxa = max3f(mxa, p0[r], p0[r + 1]); mxb = max3f(mxb, p0[r + 2], p0[r + 3]); mxa = max3f(mxa, p1[r], p1[r + 1]); mxb = max3f(mxb, p1[r + 2], p1[r + 3]); }
;         float mx = fmaxf(mxa, mxb);
;         if (__any(mx > 8.f)) {
;             mx = fmaxf(mx, __shfl_xor(mx, 32));
;             const float dl = fmaxf(mx, 0.f); mhat += dl;
;             const float f = __builtin_amdgcn_exp2f(-dl);
; #pragma unroll
;             for (int r = 0; r < 16; ++r) { p0[r] -= dl; p1[r] -= dl; negm[r] = -mhat; }
;             l *= f;
; #pragma unroll
;             for (int d = 0; d < NDT; ++d)
; #pragma unroll
;                 for (int r = 0; r < 16; ++r) o[d][r] *= f;
;         }
.LBB0_590:
	ds_read_b128 v[82:85], v179
	ds_read_b128 v[152:155], v179 offset:32
	ds_read_b128 v[156:159], v179 offset:4608
	ds_read_b128 v[160:163], v179 offset:4640
	v_cvt_f32_u32_e32 v150, v177
	s_waitcnt lgkmcnt(3)
	v_mfma_f32_32x32x16_bf16 v[98:113], v[82:85], v[114:117], v[66:81]
	v_sub_f32_e32 v182, v176, v150
	v_add_f32_e32 v183, -1.0, v182
	s_waitcnt lgkmcnt(1)
	v_mfma_f32_32x32x16_bf16 v[82:97], v[156:159], v[114:117], v[66:81]
	v_mfma_f32_32x32x16_bf16 v[98:113], v[152:155], v[118:121], v[98:113]
	ds_read_b128 v[152:155], v179 offset:64
	ds_read_b128 v[156:159], v179 offset:96
	s_waitcnt lgkmcnt(2)
	v_mfma_f32_32x32x16_bf16 v[82:97], v[160:163], v[118:121], v[82:97]
	s_waitcnt lgkmcnt(1)
	v_mfma_f32_32x32x16_bf16 v[98:113], v[152:155], v[122:125], v[98:113]
	ds_read_b128 v[152:155], v179 offset:4672
	ds_read_b128 v[160:163], v179 offset:4704
	s_waitcnt lgkmcnt(1)
	v_mfma_f32_32x32x16_bf16 v[82:97], v[152:155], v[122:125], v[82:97]
	v_and_b32_e32 v152, 0x7fffffff, v182
	v_and_b32_e32 v153, 0x7fffffff, v183
	v_mfma_f32_32x32x16_bf16 v[98:113], v[156:159], v[126:129], v[98:113]
	s_waitcnt lgkmcnt(0)
	v_mfma_f32_32x32x16_bf16 v[82:97], v[160:163], v[126:129], v[82:97]
	s_nop 15
	s_nop 7
	s_nop 9
	v_pk_fma_f32 v[156:157], v[142:143], v[152:153], v[98:99] neg_lo:[1,0,0] neg_hi:[1,0,0]
	v_pk_add_f32 v[98:99], v[182:183], s[6:7] op_sel_hi:[1,0]
	s_nop 0
	v_fma_f32 v99, -v143, |v99|, v83
	v_fma_f32 v98, -v142, |v98|, v82
	v_pk_add_f32 v[82:83], v[182:183], s[8:9] op_sel_hi:[0,1]
	v_fma_f32 v161, -v143, |v83|, v101
	v_fma_f32 v160, -v142, |v82|, v100
	v_pk_add_f32 v[82:83], v[82:83], s[6:7] op_sel_hi:[1,0]
	v_fma_f32 v153, -v143, |v83|, v85
	v_fma_f32 v152, -v142, |v82|, v84
	v_pk_add_f32 v[82:83], v[182:183], s[10:11] op_sel_hi:[0,1]
	v_fma_f32 v165, -v143, |v83|, v103
	v_fma_f32 v164, -v142, |v82|, v102
	v_pk_add_f32 v[82:83], v[82:83], s[6:7] op_sel_hi:[1,0]
	v_fma_f32 v103, -v143, |v83|, v87
	v_fma_f32 v102, -v142, |v82|, v86
	v_pk_add_f32 v[82:83], v[182:183], s[22:23] op_sel_hi:[0,1]
	v_fma_f32 v167, -v143, |v83|, v105
	v_fma_f32 v166, -v142, |v82|, v104
	v_pk_add_f32 v[82:83], v[82:83], s[6:7] op_sel_hi:[1,0]
	v_fma_f32 v155, -v143, |v83|, v89
	v_fma_f32 v154, -v142, |v82|, v88
	v_pk_add_f32 v[82:83], v[182:183], s[34:35] op_sel_hi:[0,1]
	v_fma_f32 v159, -v143, |v83|, v107
	v_fma_f32 v158, -v142, |v82|, v106
	v_pk_add_f32 v[82:83], v[82:83], s[6:7] op_sel_hi:[1,0]
	v_fma_f32 v101, -v143, |v83|, v91
	v_fma_f32 v100, -v142, |v82|, v90
	v_pk_add_f32 v[82:83], v[182:183], s[36:37] op_sel_hi:[0,1]
	v_fma_f32 v163, -v143, |v83|, v109
	v_fma_f32 v162, -v142, |v82|, v108
	v_pk_add_f32 v[82:83], v[82:83], s[6:7] op_sel_hi:[1,0]
	v_fma_f32 v105, -v143, |v83|, v93
	v_fma_f32 v104, -v142, |v82|, v92
	v_pk_add_f32 v[82:83], v[182:183], s[38:39] op_sel_hi:[0,1]
	v_fma_f32 v111, -v143, |v83|, v111
	v_fma_f32 v110, -v142, |v82|, v110
	v_pk_add_f32 v[82:83], v[82:83], s[6:7] op_sel_hi:[1,0]
	v_fma_f32 v107, -v143, |v83|, v95
	v_fma_f32 v106, -v142, |v82|, v94
	v_pk_add_f32 v[82:83], v[182:183], s[40:41] op_sel_hi:[0,1]
	v_fma_f32 v113, -v143, |v83|, v113
	v_fma_f32 v112, -v142, |v82|, v112
	v_pk_add_f32 v[82:83], v[82:83], s[6:7] op_sel_hi:[1,0]
	v_fma_f32 v109, -v143, |v83|, v97
	v_fma_f32 v108, -v142, |v82|, v96
	v_max3_f32 v82, v156, v157, v98
	v_max3_f32 v83, v160, v161, v99
	v_max3_f32 v82, v82, v152, v153
	v_max3_f32 v83, v83, v166, v167
	v_max3_f32 v82, v82, v164, v165
	v_max3_f32 v83, v83, v154, v155
	v_max3_f32 v82, v82, v102, v103
	v_max3_f32 v83, v83, v162, v163
	v_max3_f32 v82, v82, v158, v159
	v_max3_f32 v83, v83, v104, v105
	v_max3_f32 v82, v82, v100, v101
	v_max3_f32 v83, v83, v112, v113
	v_max3_f32 v82, v82, v110, v111
	v_max3_f32 v83, v83, v108, v109
	v_max3_f32 v82, v82, v106, v107
	v_max_f32_e32 v83, v83, v83
	v_max_f32_e32 v82, v82, v82
	v_max_f32_e32 v82, v82, v83
	v_cmp_gt_f32_e32 vcc, 0xc3400000, v82
	s_cmp_eq_u64 vcc, exec
	s_cbranch_scc1 .Lsk1_p4a2
	v_cmp_lt_f32_e32 vcc, s44, v82
	s_cbranch_vccz .LBB0_592
	ds_bpermute_b32 v66, v168, v82
	s_waitcnt lgkmcnt(0)
	v_max3_f32 v67, v82, v66, 0
	v_exp_f32_e64 v66, -v67
	v_add_f32_e32 v180, v180, v67
	v_xor_b32_e32 v82, 0x80000000, v180
	v_sub_f32_e32 v98, v98, v67
	v_sub_f32_e32 v99, v99, v67
	v_sub_f32_e32 v152, v152, v67
	v_sub_f32_e32 v153, v153, v67
	v_sub_f32_e32 v102, v102, v67
	v_sub_f32_e32 v103, v103, v67
	v_sub_f32_e32 v154, v154, v67
	v_sub_f32_e32 v155, v155, v67
	v_sub_f32_e32 v100, v100, v67
	v_sub_f32_e32 v101, v101, v67
	v_sub_f32_e32 v104, v104, v67
	v_sub_f32_e32 v105, v105, v67
	v_sub_f32_e32 v106, v106, v67
	v_sub_f32_e32 v107, v107, v67
	v_sub_f32_e32 v108, v108, v67
	v_sub_f32_e32 v109, v109, v67
	v_pk_mul_f32 v[16:17], v[16:17], v[66:67] op_sel_hi:[1,0]
	v_pk_mul_f32 v[14:15], v[14:15], v[66:67] op_sel_hi:[1,0]
	v_pk_mul_f32 v[12:13], v[12:13], v[66:67] op_sel_hi:[1,0]
	v_pk_mul_f32 v[10:11], v[10:11], v[66:67] op_sel_hi:[1,0]
	v_pk_mul_f32 v[8:9], v[8:9], v[66:67] op_sel_hi:[1,0]
	v_pk_mul_f32 v[6:7], v[6:7], v[66:67] op_sel_hi:[1,0]
	v_pk_mul_f32 v[4:5], v[4:5], v[66:67] op_sel_hi:[1,0]
	v_pk_mul_f32 v[2:3], v[2:3], v[66:67] op_sel_hi:[1,0]
	v_pk_mul_f32 v[32:33], v[32:33], v[66:67] op_sel_hi:[1,0]
	v_pk_mul_f32 v[30:31], v[30:31], v[66:67] op_sel_hi:[1,0]
	v_pk_mul_f32 v[28:29], v[28:29], v[66:67] op_sel_hi:[1,0]
	v_pk_mul_f32 v[26:27], v[26:27], v[66:67] op_sel_hi:[1,0]
	v_pk_mul_f32 v[24:25], v[24:25], v[66:67] op_sel_hi:[1,0]
	v_pk_mul_f32 v[22:23], v[22:23], v[66:67] op_sel_hi:[1,0]
	v_pk_mul_f32 v[20:21], v[20:21], v[66:67] op_sel_hi:[1,0]
	v_pk_mul_f32 v[18:19], v[18:19], v[66:67] op_sel_hi:[1,0]
	v_pk_mul_f32 v[48:49], v[48:49], v[66:67] op_sel_hi:[1,0]
; #define LAS __attribute__((address_space(3)))
; __device__ __forceinline__ unsigned cvtpk(float lo, float hi) { typedef __bf16 bf2 __attribute__((ext_vector_type(2))); f32x2 v = {lo, hi}; bf2 b = __builtin_convertvector(v, bf2); return __builtin_bit_cast(unsigned, b); }
; template <int DQK, int DV, bool BIAS> ...
;     ...
;             for (int r = 0; r < 16; ++r) { p0[r] -= dl; p1[r] -= dl; negm[r] = -mhat; }
;             l *= f;
; #pragma unroll
;             for (int d = 0; d < NDT; ++d)
; #pragma unroll
;                 for (int r = 0; r < 16; ++r) o[d][r] *= f;
;         }
;         if (!isY) {
;             const LAS unsigned char* vbase = lds + VOFF + vcur * VBUF + (4 * hi + ((lane & 15) >> 2)) * 64 + ((lane >> 4) & 1) * 32 + (lane & 3) * 8;
;             float ls = 0.f;
; #pragma unroll
;             for (int hs = 0; hs < 4; ++hs) {
;                 float e[8];
; #pragma unroll
;                 for (int j = 0; j < 8; ++j) { e[j] = __builtin_amdgcn_exp2f(hs < 2 ? p0[8 * (hs & 1) + j] : p1[8 * (hs & 1) + j]); ls += e[j]; }
;                 pw[hs].x = cvtpk(e[0], e[1]); pw[hs].y = cvtpk(e[2], e[3]); pw[hs].z = cvtpk(e[4], e[5]); pw[hs].w = cvtpk(e[6], e[7]);
;                 const bf16x8 pbv = __builtin_bit_cast(bf16x8, pw[hs]);
; #pragma unroll
;                 for (int d = 0; d < NDT; ++d) { const LAS unsigned char* vp = vbase + d * 4096 + hs * 1024;
;                     const v4i16_t a0 = __builtin_amdgcn_ds_read_tr16_b64_v4i16((LAS v4i16_t*)vp), a1 = __builtin_amdgcn_ds_read_tr16_b64_v4i16((LAS v4i16_t*)(vp + 512));
;                     const bf16x8 av = {a0[0], a0[1], a0[2], a0[3], a1[0], a1[1], a1[2], a1[3]};
;                     o[d] = __builtin_amdgcn_mfma_f32_32x32x16_bf16(av, pbv, o[d], 0, 0, 0); }
	v_pk_mul_f32 v[46:47], v[46:47], v[66:67] op_sel_hi:[1,0]
	v_pk_mul_f32 v[44:45], v[44:45], v[66:67] op_sel_hi:[1,0]
	v_pk_mul_f32 v[42:43], v[42:43], v[66:67] op_sel_hi:[1,0]
	v_pk_mul_f32 v[40:41], v[40:41], v[66:67] op_sel_hi:[1,0]
	v_pk_mul_f32 v[38:39], v[38:39], v[66:67] op_sel_hi:[1,0]
	v_pk_mul_f32 v[36:37], v[36:37], v[66:67] op_sel_hi:[1,0]
	v_pk_mul_f32 v[34:35], v[34:35], v[66:67] op_sel_hi:[1,0]
	v_pk_mul_f32 v[64:65], v[64:65], v[66:67] op_sel_hi:[1,0]
	v_pk_mul_f32 v[62:63], v[62:63], v[66:67] op_sel_hi:[1,0]
	v_pk_mul_f32 v[60:61], v[60:61], v[66:67] op_sel_hi:[1,0]
	v_pk_mul_f32 v[58:59], v[58:59], v[66:67] op_sel_hi:[1,0]
	v_pk_mul_f32 v[56:57], v[56:57], v[66:67] op_sel_hi:[1,0]
	v_pk_mul_f32 v[54:55], v[54:55], v[66:67] op_sel_hi:[1,0]
	v_pk_mul_f32 v[52:53], v[52:53], v[66:67] op_sel_hi:[1,0]
	v_pk_mul_f32 v[50:51], v[50:51], v[66:67] op_sel_hi:[1,0]
	v_sub_f32_e32 v156, v156, v67
	v_sub_f32_e32 v157, v157, v67
	v_sub_f32_e32 v160, v160, v67
	v_sub_f32_e32 v161, v161, v67
	v_sub_f32_e32 v164, v164, v67
	v_sub_f32_e32 v165, v165, v67
	v_sub_f32_e32 v166, v166, v67
	v_sub_f32_e32 v167, v167, v67
	v_sub_f32_e32 v158, v158, v67
	v_sub_f32_e32 v159, v159, v67
	v_sub_f32_e32 v162, v162, v67
	v_sub_f32_e32 v163, v163, v67
	v_sub_f32_e32 v110, v110, v67
	v_sub_f32_e32 v111, v111, v67
	v_sub_f32_e32 v112, v112, v67
	v_sub_f32_e32 v113, v113, v67
	v_mul_f32_e32 v151, v151, v66
	v_mov_b32_e32 v66, v82
	v_mov_b32_e32 v67, v82
	v_mov_b32_e32 v68, v82
	v_mov_b32_e32 v69, v82
	v_mov_b32_e32 v70, v82
	v_mov_b32_e32 v71, v82
	v_mov_b32_e32 v72, v82
	v_mov_b32_e32 v73, v82
	v_mov_b32_e32 v74, v82
	v_mov_b32_e32 v75, v82
	v_mov_b32_e32 v76, v82
	v_mov_b32_e32 v77, v82
	v_mov_b32_e32 v78, v82
	v_mov_b32_e32 v79, v82
	v_mov_b32_e32 v80, v82
	v_mov_b32_e32 v81, v82
	s_branch .LBB0_593
.Lsk1_p4a2:
	v_mov_b32_e32 v150, 0
	v_mov_b32_e32 v152, 0
	v_mov_b32_e32 v153, 0
	v_mov_b32_e32 v154, 0
	v_mov_b32_e32 v155, 0
	v_mov_b32_e32 v156, 0
	v_mov_b32_e32 v157, 0
	v_mov_b32_e32 v158, 0
	v_mov_b32_e32 v159, 0
	v_mov_b32_e32 v160, 0
	v_mov_b32_e32 v161, 0
	v_mov_b32_e32 v162, 0
	v_mov_b32_e32 v163, 0
	v_mov_b32_e32 v164, 0
	v_mov_b32_e32 v165, 0
	v_mov_b32_e32 v166, 0
	v_mov_b32_e32 v167, 0
	v_mov_b32_e32 v181, 0
	v_mov_b32_e32 v182, 0
	v_mov_b32_e32 v183, 0
	v_mov_b32_e32 v184, 0
	v_mov_b32_e32 v185, 0
	v_mov_b32_e32 v186, 0
	v_mov_b32_e32 v187, 0
	v_mov_b32_e32 v188, 0
	v_mov_b32_e32 v189, 0
	v_mov_b32_e32 v190, 0
	v_mov_b32_e32 v191, 0
	v_mov_b32_e32 v192, 0
	v_mov_b32_e32 v193, 0
	v_mov_b32_e32 v194, 0
	v_mov_b32_e32 v195, 0
	s_branch .Lend1_p4a2
.LBB0_592:
.LBB0_593:
	v_exp_f32_e32 v156, v156
	v_exp_f32_e32 v157, v157
	v_exp_f32_e32 v160, v160
	v_exp_f32_e32 v161, v161
	v_exp_f32_e32 v164, v164
	v_exp_f32_e32 v150, v165
	ds_read_b64_tr_b16 v[182:183], v178 offset:18432
	ds_read_b64_tr_b16 v[184:185], v178 offset:18944
	v_exp_f32_e32 v165, v166
	v_exp_f32_e32 v166, v167
	ds_read_b64_tr_b16 v[190:191], v178 offset:22528
	ds_read_b64_tr_b16 v[192:193], v178 offset:23040
	v_cvt_pk_bf16_f32 v186, v156, v157
	v_cvt_pk_bf16_f32 v187, v160, v161
	v_cvt_pk_bf16_f32 v188, v164, v150
	v_cvt_pk_bf16_f32 v189, v165, v166
	s_waitcnt lgkmcnt(2)
	s_nop 0
	v_mfma_f32_32x32x16_bf16 v[2:17], v[182:185], v[186:189], v[2:17]
	s_waitcnt lgkmcnt(0)
	v_mfma_f32_32x32x16_bf16 v[18:33], v[190:193], v[186:189], v[18:33]
	ds_read_b64_tr_b16 v[182:183], v178 offset:26624
	ds_read_b64_tr_b16 v[184:185], v178 offset:27136
	ds_read_b64_tr_b16 v[190:191], v178 offset:30720
	ds_read_b64_tr_b16 v[192:193], v178 offset:31232
	s_waitcnt lgkmcnt(2)
	v_mfma_f32_32x32x16_bf16 v[34:49], v[182:185], v[186:189], v[34:49]
	s_waitcnt lgkmcnt(0)
	v_mfma_f32_32x32x16_bf16 v[50:65], v[190:193], v[186:189], v[50:65]
	v_exp_f32_e32 v167, v158
	v_exp_f32_e32 v181, v159
	v_exp_f32_e32 v182, v162
	v_exp_f32_e32 v158, v163
	v_exp_f32_e32 v159, v110
	v_exp_f32_e32 v162, v111
	ds_read_b64_tr_b16 v[184:185], v178 offset:19456
	ds_read_b64_tr_b16 v[186:187], v178 offset:19968
	v_exp_f32_e32 v163, v112
	v_exp_f32_e32 v183, v113
	ds_read_b64_tr_b16 v[188:189], v178 offset:23552
	ds_read_b64_tr_b16 v[190:191], v178 offset:24064
	v_cvt_pk_bf16_f32 v110, v167, v181
	v_cvt_pk_bf16_f32 v111, v182, v158
	v_cvt_pk_bf16_f32 v112, v159, v162
	v_cvt_pk_bf16_f32 v113, v163, v183
	s_waitcnt lgkmcnt(2)
	s_nop 0
	v_mfma_f32_32x32x16_bf16 v[2:17], v[184:187], v[110:113], v[2:17]
	s_waitcnt lgkmcnt(0)
	v_mfma_f32_32x32x16_bf16 v[18:33], v[188:191], v[110:113], v[18:33]
	ds_read_b64_tr_b16 v[184:185], v178 offset:27648
	ds_read_b64_tr_b16 v[186:187], v178 offset:28160
	ds_read_b64_tr_b16 v[188:189], v178 offset:31744
	ds_read_b64_tr_b16 v[190:191], v178 offset:32256
	s_waitcnt lgkmcnt(2)
	v_mfma_f32_32x32x16_bf16 v[34:49], v[184:187], v[110:113], v[34:49]
	s_waitcnt lgkmcnt(0)
	v_mfma_f32_32x32x16_bf16 v[50:65], v[188:191], v[110:113], v[50:65]
	v_exp_f32_e32 v184, v98
	v_exp_f32_e32 v185, v99
	v_exp_f32_e32 v152, v152
	v_exp_f32_e32 v153, v153
	v_exp_f32_e32 v186, v102
	ds_read_b64_tr_b16 v[110:111], v178 offset:20480
	ds_read_b64_tr_b16 v[112:113], v178 offset:20992
	v_exp_f32_e32 v187, v103
	v_exp_f32_e32 v154, v154
	v_exp_f32_e32 v155, v155
	v_cvt_pk_bf16_f32 v188, v184, v185
	v_cvt_pk_bf16_f32 v189, v152, v153
	v_cvt_pk_bf16_f32 v190, v186, v187
	v_cvt_pk_bf16_f32 v191, v154, v155
	ds_read_b64_tr_b16 v[194:195], v178 offset:33280
	s_waitcnt lgkmcnt(1)
	v_mfma_f32_32x32x16_bf16 v[2:17], v[110:113], v[188:191], v[2:17]
	ds_read_b64_tr_b16 v[110:111], v178 offset:24576
	ds_read_b64_tr_b16 v[112:113], v178 offset:25088
	ds_read_b64_tr_b16 v[196:197], v178 offset:28672
	ds_read_b64_tr_b16 v[198:199], v178 offset:29184
	ds_read_b64_tr_b16 v[192:193], v178 offset:32768
	s_waitcnt lgkmcnt(3)
; #define LAS __attribute__((address_space(3)))
; template <int DQK, int DV, bool BIAS> ...
;     ...
;         __syncthreads();
;         if (g + 1 < NG) {
; #pragma unroll
;             for (int j = 0; j < TPB; ++j) ATT_STORE((pair ^ 1) * TPB + j, j);
;             if (g + 2 < NG) {
; #pragma unroll
;                 for (int j = 0; j < TPB; ++j) ATT_LOAD((g + 2) * TPB + j, j);
;             }
;         }
; #pragma unroll
;       for (int sub = 0; sub < TPB; ++sub) {
;         const int t = g * TPB + sub, buf = pair * TPB + sub, vcur = buf;
;         f32x16 p0, p1;
;         const LAS unsigned char* kb = lds + buf * KBUF + r32 * KP + hi * 16;
; #pragma unroll
;         for (int ks = 0; ks < NKS; ++ks) {
;             const bf16x8 k0 = *(const LAS bf16x8*)(kb + ks * 32), k1 = *(const LAS bf16x8*)(kb + 32 * KP + ks * 32);
;             if (ks == 0) { p0 = __builtin_amdgcn_mfma_f32_32x32x16_bf16(k0, qf[0], negm, 0, 0, 0); p1 = __builtin_amdgcn_mfma_f32_32x32x16_bf16(k1, qf[0], negm, 0, 0, 0); }
;             else { p0 = __builtin_amdgcn_mfma_f32_32x32x16_bf16(k0, qf[ks], p0, 0, 0, 0); p1 = __builtin_amdgcn_mfma_f32_32x32x16_bf16(k1, qf[ks], p1, 0, 0, 0); }
;         }
;         if (BIAS) {
;             asm volatile("s_nop 15\n\ts_nop 7" : "+v"(p0), "+v"(p1));
;             const float d0 = qp - (float)(t * 64 + 4 * hi);
; #pragma unroll
;             for (int r = 0; r < 16; ++r) { const float dk = d0 - (float)((r & 3) + 8 * (r >> 2)); p0[r] = p0[r] - sl2 * fabsf(dk); p1[r] = p1[r] - sl2 * fabsf(dk - 32.f); }
	v_mfma_f32_32x32x16_bf16 v[18:33], v[110:113], v[188:191], v[18:33]
	s_waitcnt lgkmcnt(1)
	v_mfma_f32_32x32x16_bf16 v[34:49], v[196:199], v[188:191], v[34:49]
	s_waitcnt lgkmcnt(0)
	v_mfma_f32_32x32x16_bf16 v[50:65], v[192:195], v[188:191], v[50:65]
	v_exp_f32_e32 v188, v100
	v_exp_f32_e32 v189, v101
	v_exp_f32_e32 v190, v104
	v_exp_f32_e32 v191, v105
	v_exp_f32_e32 v192, v106
	ds_read_b64_tr_b16 v[98:99], v178 offset:21504
	ds_read_b64_tr_b16 v[100:101], v178 offset:22016
	v_exp_f32_e32 v195, v107
	v_exp_f32_e32 v193, v108
	v_exp_f32_e32 v194, v109
	v_cvt_pk_bf16_f32 v102, v188, v189
	v_cvt_pk_bf16_f32 v103, v190, v191
	v_cvt_pk_bf16_f32 v104, v192, v195
	v_cvt_pk_bf16_f32 v105, v193, v194
	ds_read_b64_tr_b16 v[108:109], v178 offset:34304
	s_waitcnt lgkmcnt(1)
	v_mfma_f32_32x32x16_bf16 v[2:17], v[98:101], v[102:105], v[2:17]
	ds_read_b64_tr_b16 v[98:99], v178 offset:25600
	ds_read_b64_tr_b16 v[100:101], v178 offset:26112
	ds_read_b64_tr_b16 v[110:111], v178 offset:29696
	ds_read_b64_tr_b16 v[112:113], v178 offset:30208
	ds_read_b64_tr_b16 v[106:107], v178 offset:33792
	s_waitcnt lgkmcnt(3)
	v_mfma_f32_32x32x16_bf16 v[18:33], v[98:101], v[102:105], v[18:33]
	s_waitcnt lgkmcnt(1)
	v_mfma_f32_32x32x16_bf16 v[34:49], v[110:113], v[102:105], v[34:49]
	s_waitcnt lgkmcnt(0)
	v_mfma_f32_32x32x16_bf16 v[50:65], v[106:109], v[102:105], v[50:65]
.Lend1_p4a2:
	s_cmp_eq_u32 s4, 0x1876000
	s_barrier
	s_cbranch_scc1 .LBB0_596
	s_andn2_b64 vcc, exec, s[42:43]
	s_waitcnt vmcnt(0)
	ds_write_b128 v174, v[138:141]
	ds_write_b128 v175, v[130:133] offset:18432
	ds_write_b128 v175, v[134:137] offset:26624
	s_cbranch_vccnz .LBB0_596
	v_lshl_add_u64 v[98:99], v[148:149], 0, s[4:5]
	v_add_co_u32_e32 v98, vcc, 0x12f000, v98
	v_lshl_add_u64 v[100:101], v[146:147], 0, s[4:5]
	s_nop 0
	v_addc_co_u32_e32 v99, vcc, 0, v99, vcc
	v_add_co_u32_e32 v100, vcc, 0x12f000, v100
	s_nop 1
	v_addc_co_u32_e32 v101, vcc, 0, v101, vcc
	global_load_dwordx4 v[130:133], v[98:99], off offset:2048
	global_load_dwordx4 v[134:137], v[100:101], off offset:2048
	v_lshl_add_u64 v[98:99], v[144:145], 0, s[4:5]
	v_add_co_u32_e32 v98, vcc, 0x12f000, v98
	s_nop 1
	v_addc_co_u32_e32 v99, vcc, 0, v99, vcc
	global_load_dwordx4 v[138:141], v[98:99], off offset:1152
.LBB0_596:
	ds_read_b128 v[196:199], v179 offset:9216
	ds_read_b128 v[200:203], v179 offset:9248
	v_add_f32_e32 v156, 0, v156
	v_add_f32_e32 v156, v157, v156
	v_add_f32_e32 v156, v160, v156
	s_waitcnt lgkmcnt(1)
	v_mfma_f32_32x32x16_bf16 v[98:113], v[196:199], v[114:117], v[66:81]
	ds_read_b128 v[196:199], v179 offset:13824
	ds_read_b128 v[204:207], v179 offset:13856
	v_add_f32_e32 v156, v161, v156
	v_add_f32_e32 v156, v164, v156
	v_add_f32_e32 v150, v150, v156
	v_add_f32_e32 v150, v165, v150
	v_add_f32_e32 v150, v166, v150
	v_add_f32_e32 v150, v167, v150
	s_waitcnt lgkmcnt(1)
	v_mfma_f32_32x32x16_bf16 v[82:97], v[196:199], v[114:117], v[66:81]
	v_add_f32_e32 v150, v181, v150
	v_add_f32_e32 v150, v182, v150
	v_add_f32_e32 v150, v158, v150
	v_add_f32_e32 v150, v159, v150
	ds_read_b128 v[164:167], v179 offset:9280
	v_add_f32_e32 v150, v162, v150
	v_add_f32_e32 v150, v163, v150
	v_mfma_f32_32x32x16_bf16 v[98:113], v[200:203], v[118:121], v[98:113]
	v_add_f32_e32 v150, v183, v150
	v_add_f32_e32 v150, v184, v150
	v_add_f32_e32 v150, v185, v150
	v_add_f32_e32 v150, v152, v150
	ds_read_b128 v[156:159], v179 offset:13888
	ds_read_b128 v[160:163], v179 offset:9312
	v_add_f32_e32 v150, v153, v150
	v_add_f32_e32 v150, v186, v150
	s_waitcnt lgkmcnt(3)
	v_mfma_f32_32x32x16_bf16 v[82:97], v[204:207], v[118:121], v[82:97]
	v_add_f32_e32 v150, v187, v150
	v_add_f32_e32 v150, v154, v150
	v_add_f32_e32 v150, v155, v150
	v_add_f32_e32 v150, v188, v150
	v_add_f32_e32 v150, v189, v150
	v_add_u32_e32 v152, 64, v177
	v_add_f32_e32 v150, v190, v150
	s_waitcnt lgkmcnt(2)
	v_mfma_f32_32x32x16_bf16 v[98:113], v[164:167], v[122:125], v[98:113]
	ds_read_b128 v[164:167], v179 offset:13920
	v_cvt_f32_u32_e32 v152, v152
	v_add_f32_e32 v150, v191, v150
	v_add_f32_e32 v150, v192, v150
	v_add_f32_e32 v150, v195, v150
	v_add_f32_e32 v150, v193, v150
	v_add_f32_e32 v150, v194, v150
	s_waitcnt lgkmcnt(2)
	v_mfma_f32_32x32x16_bf16 v[82:97], v[156:159], v[122:125], v[82:97]
	v_add_f32_e32 v158, v151, v150
	s_waitcnt lgkmcnt(1)
	v_mfma_f32_32x32x16_bf16 v[98:113], v[160:163], v[126:129], v[98:113]
	v_sub_f32_e32 v160, v176, v152
	v_add_f32_e32 v161, -1.0, v160
	v_and_b32_e32 v150, 0x7fffffff, v160
	v_and_b32_e32 v151, 0x7fffffff, v161
	s_waitcnt lgkmcnt(0)
; __device__ __forceinline__ float max3f(float a, float b, float c) { float r; asm("v_max3_f32 %0, %1, %2, %3" : "=v"(r) : "v"(a), "v"(b), "v"(c)); return r; }
; template <int DQK, int DV, bool BIAS> ...
;     ...
;             else { p0 = __builtin_amdgcn_mfma_f32_32x32x16_bf16(k0, qf[ks], p0, 0, 0, 0); p1 = __builtin_amdgcn_mfma_f32_32x32x16_bf16(k1, qf[ks], p1, 0, 0, 0); }
;         }
;         if (BIAS) {
;             asm volatile("s_nop 15\n\ts_nop 7" : "+v"(p0), "+v"(p1));
;             const float d0 = qp - (float)(t * 64 + 4 * hi);
; #pragma unroll
;             for (int r = 0; r < 16; ++r) { const float dk = d0 - (float)((r & 3) + 8 * (r >> 2)); p0[r] = p0[r] - sl2 * fabsf(dk); p1[r] = p1[r] - sl2 * fabsf(dk - 32.f); }
;         } else {
;             asm volatile("s_nop 15\n\ts_nop 7" : "+v"(p0), "+v"(p1));
;         }
;         float mxa = max3f(p0[0], p0[1], p1[0]), mxb = max3f(p0[2], p0[3], p1[1]); mxa = max3f(mxa, p1[2], p1[3]);
; #pragma unroll
;         for (int r = 4; r < 16; r += 4) { mxa = max3f(mxa, p0[r], p0[r + 1]); mxb = max3f(mxb, p0[r + 2], p0[r + 3]); mxa = max3f(mxa, p1[r], p1[r + 1]); mxb = max3f(mxb, p1[r + 2], p1[r + 3]); }
;         float mx = fmaxf(mxa, mxb);
;         if (__any(mx > 8.f)) {
;             mx = fmaxf(mx, __shfl_xor(mx, 32));
;             const float dl = fmaxf(mx, 0.f); mhat += dl;
;             const float f = __builtin_amdgcn_exp2f(-dl);
; #pragma unroll
;             for (int r = 0; r < 16; ++r) { p0[r] -= dl; p1[r] -= dl; negm[r] = -mhat; }
;             l *= f;
; #pragma unroll
;             for (int d = 0; d < NDT; ++d)
; #pragma unroll
;                 for (int r = 0; r < 16; ++r) o[d][r] *= f;
;         }
	v_mfma_f32_32x32x16_bf16 v[82:97], v[164:167], v[126:129], v[82:97]
	s_nop 15
	s_nop 7
	s_nop 5
	v_pk_fma_f32 v[150:151], v[142:143], v[150:151], v[98:99] neg_lo:[1,0,0] neg_hi:[1,0,0]
	v_pk_add_f32 v[98:99], v[160:161], s[6:7] op_sel_hi:[1,0]
	s_nop 0
	v_fma_f32 v83, -v143, |v99|, v83
	v_fma_f32 v82, -v142, |v98|, v82
	s_nop 0
	v_pk_add_f32 v[98:99], v[160:161], s[8:9] op_sel_hi:[0,1]
	v_fma_f32 v153, -v143, |v99|, v101
	v_fma_f32 v152, -v142, |v98|, v100
	v_pk_add_f32 v[98:99], v[98:99], s[6:7] op_sel_hi:[1,0]
	v_fma_f32 v99, -v143, |v99|, v85
	v_fma_f32 v98, -v142, |v98|, v84
	v_pk_add_f32 v[84:85], v[160:161], s[10:11] op_sel_hi:[0,1]
	v_fma_f32 v155, -v143, |v85|, v103
	v_fma_f32 v154, -v142, |v84|, v102
	v_pk_add_f32 v[84:85], v[84:85], s[6:7] op_sel_hi:[1,0]
	v_fma_f32 v101, -v143, |v85|, v87
	v_fma_f32 v100, -v142, |v84|, v86
	v_pk_add_f32 v[84:85], v[160:161], s[22:23] op_sel_hi:[0,1]
	v_fma_f32 v157, -v143, |v85|, v105
	v_fma_f32 v156, -v142, |v84|, v104
	v_pk_add_f32 v[84:85], v[84:85], s[6:7] op_sel_hi:[1,0]
	v_fma_f32 v103, -v143, |v85|, v89
	v_fma_f32 v102, -v142, |v84|, v88
	v_pk_add_f32 v[84:85], v[160:161], s[34:35] op_sel_hi:[0,1]
	v_fma_f32 v105, -v143, |v85|, v107
	v_fma_f32 v104, -v142, |v84|, v106
	v_pk_add_f32 v[86:87], v[160:161], s[36:37] op_sel_hi:[0,1]
	v_pk_add_f32 v[84:85], v[84:85], s[6:7] op_sel_hi:[1,0]
	v_fma_f32 v107, -v143, |v87|, v109
	v_fma_f32 v106, -v142, |v86|, v108
	v_fma_f32 v85, -v143, |v85|, v91
	v_fma_f32 v84, -v142, |v84|, v90
	v_pk_add_f32 v[86:87], v[86:87], s[6:7] op_sel_hi:[1,0]
	v_pk_add_f32 v[88:89], v[160:161], s[38:39] op_sel_hi:[0,1]
	v_fma_f32 v87, -v143, |v87|, v93
	v_fma_f32 v86, -v142, |v86|, v92
	v_fma_f32 v93, -v143, |v89|, v111
	v_fma_f32 v92, -v142, |v88|, v110
	v_pk_add_f32 v[88:89], v[88:89], s[6:7] op_sel_hi:[1,0]
	v_fma_f32 v89, -v143, |v89|, v95
	v_fma_f32 v88, -v142, |v88|, v94
	v_pk_add_f32 v[90:91], v[160:161], s[40:41] op_sel_hi:[0,1]
	v_fma_f32 v95, -v143, |v91|, v113
	v_fma_f32 v94, -v142, |v90|, v112
	v_pk_add_f32 v[90:91], v[90:91], s[6:7] op_sel_hi:[1,0]
	v_fma_f32 v91, -v143, |v91|, v97
	v_fma_f32 v90, -v142, |v90|, v96
	v_max3_f32 v96, v150, v151, v82
	v_max3_f32 v97, v152, v153, v83
	v_max3_f32 v96, v96, v98, v99
	v_max3_f32 v97, v97, v156, v157
	v_max3_f32 v96, v96, v154, v155
	v_max3_f32 v97, v97, v102, v103
	v_max3_f32 v96, v96, v100, v101
	v_max3_f32 v97, v97, v106, v107
	v_max3_f32 v96, v96, v104, v105
	v_max3_f32 v97, v97, v86, v87
	v_max3_f32 v96, v96, v84, v85
	v_max3_f32 v97, v97, v94, v95
	v_max3_f32 v96, v96, v92, v93
	v_max3_f32 v97, v97, v90, v91
	v_max3_f32 v96, v96, v88, v89
	v_max_f32_e32 v97, v97, v97
	v_max_f32_e32 v96, v96, v96
	v_max_f32_e32 v96, v96, v97
	v_cmp_gt_f32_e32 vcc, 0xc3400000, v96
	s_cmp_eq_u64 vcc, exec
	s_cbranch_scc1 .Lsk2_p4a2
	v_cmp_lt_f32_e32 vcc, s44, v96
	s_cbranch_vccz .LBB0_587
	ds_bpermute_b32 v66, v168, v96
	s_waitcnt lgkmcnt(0)
	v_max3_f32 v67, v96, v66, 0
	v_exp_f32_e64 v68, -v67
	v_add_f32_e32 v180, v180, v67
	v_xor_b32_e32 v66, 0x80000000, v180
	v_sub_f32_e32 v82, v82, v67
	v_sub_f32_e32 v83, v83, v67
	v_sub_f32_e32 v98, v98, v67
	v_sub_f32_e32 v99, v99, v67
	v_sub_f32_e32 v100, v100, v67
	v_sub_f32_e32 v101, v101, v67
	v_sub_f32_e32 v102, v102, v67
	v_sub_f32_e32 v103, v103, v67
	v_sub_f32_e32 v84, v84, v67
	v_sub_f32_e32 v85, v85, v67
	v_sub_f32_e32 v86, v86, v67
	v_sub_f32_e32 v87, v87, v67
	v_sub_f32_e32 v88, v88, v67
	v_sub_f32_e32 v89, v89, v67
	v_sub_f32_e32 v90, v90, v67
	v_sub_f32_e32 v91, v91, v67
	v_pk_mul_f32 v[16:17], v[16:17], v[68:69] op_sel_hi:[1,0]
	v_pk_mul_f32 v[14:15], v[14:15], v[68:69] op_sel_hi:[1,0]
	v_pk_mul_f32 v[12:13], v[12:13], v[68:69] op_sel_hi:[1,0]
	v_pk_mul_f32 v[10:11], v[10:11], v[68:69] op_sel_hi:[1,0]
	v_pk_mul_f32 v[8:9], v[8:9], v[68:69] op_sel_hi:[1,0]
	v_pk_mul_f32 v[6:7], v[6:7], v[68:69] op_sel_hi:[1,0]
	v_pk_mul_f32 v[4:5], v[4:5], v[68:69] op_sel_hi:[1,0]
	v_pk_mul_f32 v[2:3], v[2:3], v[68:69] op_sel_hi:[1,0]
	v_pk_mul_f32 v[32:33], v[32:33], v[68:69] op_sel_hi:[1,0]
	v_pk_mul_f32 v[30:31], v[30:31], v[68:69] op_sel_hi:[1,0]
	v_pk_mul_f32 v[28:29], v[28:29], v[68:69] op_sel_hi:[1,0]
	v_pk_mul_f32 v[26:27], v[26:27], v[68:69] op_sel_hi:[1,0]
	v_pk_mul_f32 v[24:25], v[24:25], v[68:69] op_sel_hi:[1,0]
	v_pk_mul_f32 v[22:23], v[22:23], v[68:69] op_sel_hi:[1,0]
	v_pk_mul_f32 v[20:21], v[20:21], v[68:69] op_sel_hi:[1,0]
	v_pk_mul_f32 v[18:19], v[18:19], v[68:69] op_sel_hi:[1,0]
	v_pk_mul_f32 v[48:49], v[48:49], v[68:69] op_sel_hi:[1,0]
	v_pk_mul_f32 v[46:47], v[46:47], v[68:69] op_sel_hi:[1,0]
	v_pk_mul_f32 v[44:45], v[44:45], v[68:69] op_sel_hi:[1,0]
	v_pk_mul_f32 v[42:43], v[42:43], v[68:69] op_sel_hi:[1,0]
	v_pk_mul_f32 v[40:41], v[40:41], v[68:69] op_sel_hi:[1,0]
	v_pk_mul_f32 v[38:39], v[38:39], v[68:69] op_sel_hi:[1,0]
	v_pk_mul_f32 v[36:37], v[36:37], v[68:69] op_sel_hi:[1,0]
	v_pk_mul_f32 v[34:35], v[34:35], v[68:69] op_sel_hi:[1,0]
	v_pk_mul_f32 v[64:65], v[64:65], v[68:69] op_sel_hi:[1,0]
	v_pk_mul_f32 v[62:63], v[62:63], v[68:69] op_sel_hi:[1,0]
	v_pk_mul_f32 v[60:61], v[60:61], v[68:69] op_sel_hi:[1,0]
	v_pk_mul_f32 v[58:59], v[58:59], v[68:69] op_sel_hi:[1,0]
	v_pk_mul_f32 v[56:57], v[56:57], v[68:69] op_sel_hi:[1,0]
	v_pk_mul_f32 v[54:55], v[54:55], v[68:69] op_sel_hi:[1,0]
	v_pk_mul_f32 v[52:53], v[52:53], v[68:69] op_sel_hi:[1,0]
	v_pk_mul_f32 v[50:51], v[50:51], v[68:69] op_sel_hi:[1,0]
	v_sub_f32_e32 v150, v150, v67
	v_sub_f32_e32 v151, v151, v67
	v_sub_f32_e32 v152, v152, v67
	v_sub_f32_e32 v153, v153, v67
	v_sub_f32_e32 v154, v154, v67
	v_sub_f32_e32 v155, v155, v67
	v_sub_f32_e32 v156, v156, v67
	v_sub_f32_e32 v157, v157, v67
	v_sub_f32_e32 v104, v104, v67
	v_sub_f32_e32 v105, v105, v67
	v_sub_f32_e32 v106, v106, v67
	v_sub_f32_e32 v107, v107, v67
	v_sub_f32_e32 v92, v92, v67
	v_sub_f32_e32 v93, v93, v67
	v_sub_f32_e32 v94, v94, v67
	v_sub_f32_e32 v95, v95, v67
	v_mul_f32_e32 v158, v158, v68
	v_mov_b32_e32 v67, v66
	v_mov_b32_e32 v68, v66
	v_mov_b32_e32 v69, v66
	v_mov_b32_e32 v70, v66
	v_mov_b32_e32 v71, v66
	v_mov_b32_e32 v72, v66
	v_mov_b32_e32 v73, v66
	v_mov_b32_e32 v74, v66
	v_mov_b32_e32 v75, v66
	v_mov_b32_e32 v76, v66
	v_mov_b32_e32 v77, v66
	v_mov_b32_e32 v78, v66
	v_mov_b32_e32 v79, v66
	v_mov_b32_e32 v80, v66
	v_mov_b32_e32 v81, v66
	s_branch .LBB0_587
